# remove redundant back-to-back s_setprio 0/1 pairs inside GEMM MFMA blocks
# baseline (speedup 1.0000x reference)
.LBB0_108:
	v_add_u32_e32 v146, s58, v172
	ds_read_b128 v[134:137], v146
	ds_read_b128 v[162:165], v146 offset:1024
	ds_read_b128 v[166:169], v146 offset:2048
	ds_read_b128 v[184:187], v146 offset:3072
	v_add_u32_e32 v146, s59, v172
	s_add_u32 s36, s26, s8
	ds_read_b128 v[188:191], v146
	ds_read_b128 v[192:195], v146 offset:1024
	ds_read_b128 v[196:199], v146 offset:2048
	ds_read_b128 v[200:203], v146 offset:3072
	s_addc_u32 s37, s27, s9
	s_add_u32 s36, s36, 0x100
	s_addc_u32 s37, s37, 0
	s_add_u32 s65, s47, s8
	s_addc_u32 s66, s63, s9
	s_cmpk_eq_i32 s8, 0x700
	s_cselect_b32 s39, s51, s37
	s_cselect_b32 s38, s50, s36
	s_cselect_b32 s37, s49, s66
	s_cselect_b32 s36, s48, s65
	v_lshl_add_u64 v[236:237], v[130:131], 0, s[8:9]
	s_add_i32 m0, s19, 0xc000
	ds_read_b128 v[204:207], v173
	ds_read_b128 v[208:211], v173 offset:1024
	ds_read_b128 v[212:215], v173 offset:2048
	ds_read_b128 v[216:219], v173 offset:3072
	ds_read_b128 v[220:223], v173 offset:4096
	ds_read_b128 v[224:227], v173 offset:5120
	ds_read_b128 v[228:231], v173 offset:6144
	ds_read_b128 v[232:235], v173 offset:7168
	global_load_lds_dwordx4 v[236:237], off
	v_lshl_add_u64 v[236:237], v[132:133], 0, s[8:9]
	s_add_i32 m0, s19, 0xe000
	s_nop 0
	global_load_lds_dwordx4 v[236:237], off
	s_waitcnt vmcnt(8)
	s_waitcnt lgkmcnt(0)
	s_barrier
	s_setprio 1
	s_waitcnt lgkmcnt(0)
	v_mfma_f32_16x16x32_bf16 v[126:129], v[134:137], v[204:207], v[126:129]
	v_mfma_f32_16x16x32_bf16 v[122:125], v[166:169], v[204:207], v[122:125]
	v_mfma_f32_16x16x32_bf16 v[118:121], v[134:137], v[212:215], v[118:121]
	v_mfma_f32_16x16x32_bf16 v[114:117], v[166:169], v[212:215], v[114:117]
	v_mfma_f32_16x16x32_bf16 v[110:113], v[134:137], v[220:223], v[110:113]
	v_mfma_f32_16x16x32_bf16 v[106:109], v[166:169], v[220:223], v[106:109]
	v_mfma_f32_16x16x32_bf16 v[102:105], v[134:137], v[228:231], v[102:105]
	v_mfma_f32_16x16x32_bf16 v[98:101], v[166:169], v[228:231], v[98:101]
	v_mfma_f32_16x16x32_bf16 v[126:129], v[162:165], v[208:211], v[126:129]
	v_mfma_f32_16x16x32_bf16 v[122:125], v[184:187], v[208:211], v[122:125]
	v_mfma_f32_16x16x32_bf16 v[118:121], v[162:165], v[216:219], v[118:121]
	v_mfma_f32_16x16x32_bf16 v[114:117], v[184:187], v[216:219], v[114:117]
	v_mfma_f32_16x16x32_bf16 v[110:113], v[162:165], v[224:227], v[110:113]
	v_mfma_f32_16x16x32_bf16 v[106:109], v[184:187], v[224:227], v[106:109]
	v_mfma_f32_16x16x32_bf16 v[102:105], v[162:165], v[232:235], v[102:105]
	v_mfma_f32_16x16x32_bf16 v[98:101], v[184:187], v[232:235], v[98:101]
	v_mfma_f32_16x16x32_bf16 v[94:97], v[188:191], v[204:207], v[94:97]
	v_mfma_f32_16x16x32_bf16 v[90:93], v[196:199], v[204:207], v[90:93]
	v_mfma_f32_16x16x32_bf16 v[86:89], v[188:191], v[212:215], v[86:89]
	v_mfma_f32_16x16x32_bf16 v[82:85], v[196:199], v[212:215], v[82:85]
	v_mfma_f32_16x16x32_bf16 v[78:81], v[188:191], v[220:223], v[78:81]
	v_mfma_f32_16x16x32_bf16 v[74:77], v[196:199], v[220:223], v[74:77]
	v_mfma_f32_16x16x32_bf16 v[70:73], v[188:191], v[228:231], v[70:73]
	v_mfma_f32_16x16x32_bf16 v[66:69], v[196:199], v[228:231], v[66:69]
	v_mfma_f32_16x16x32_bf16 v[94:97], v[192:195], v[208:211], v[94:97]
	v_mfma_f32_16x16x32_bf16 v[90:93], v[200:203], v[208:211], v[90:93]
	v_mfma_f32_16x16x32_bf16 v[86:89], v[192:195], v[216:219], v[86:89]
	v_mfma_f32_16x16x32_bf16 v[82:85], v[200:203], v[216:219], v[82:85]
	v_mfma_f32_16x16x32_bf16 v[78:81], v[192:195], v[224:227], v[78:81]
	v_mfma_f32_16x16x32_bf16 v[74:77], v[200:203], v[224:227], v[74:77]
	v_mfma_f32_16x16x32_bf16 v[70:73], v[192:195], v[232:235], v[70:73]
	v_mfma_f32_16x16x32_bf16 v[66:69], v[200:203], v[232:235], v[66:69]
	s_setprio 0
	s_barrier
	s_add_i32 s65, s58, s18
	v_lshl_add_u64 v[236:237], s[36:37], 0, v[138:139]
	s_mov_b32 m0, s65
	ds_read_b128 v[204:207], v173 offset:16384
	ds_read_b128 v[208:211], v173 offset:17408
	ds_read_b128 v[212:215], v173 offset:18432
	ds_read_b128 v[216:219], v173 offset:19456
	ds_read_b128 v[220:223], v173 offset:20480
	ds_read_b128 v[224:227], v173 offset:21504
	ds_read_b128 v[228:231], v173 offset:22528
	ds_read_b128 v[232:235], v173 offset:23552
	global_load_lds_dwordx4 v[236:237], off
	s_add_i32 m0, s65, 0x2000
	s_add_u32 s66, s36, 0x40000
	v_lshl_add_u64 v[238:239], s[36:37], 0, v[140:141]
	s_addc_u32 s67, s37, 0
	s_add_i32 s65, s59, s18
	global_load_lds_dwordx4 v[238:239], off
	v_lshl_add_u64 v[240:241], s[66:67], 0, v[138:139]
	s_mov_b32 m0, s65
	v_lshl_add_u64 v[242:243], s[38:39], 0, v[144:145]
	global_load_lds_dwordx4 v[240:241], off
	v_lshl_add_u64 v[240:241], s[66:67], 0, v[140:141]
	s_add_i32 m0, s65, 0x2000
	s_nop 0
	global_load_lds_dwordx4 v[240:241], off
	v_lshl_add_u64 v[240:241], s[38:39], 0, v[142:143]
	s_mov_b32 m0, s19
	s_nop 0
	global_load_lds_dwordx4 v[240:241], off
	s_mov_b32 m0, s24
	s_nop 0
	global_load_lds_dwordx4 v[242:243], off
	s_waitcnt vmcnt(8)
	s_waitcnt lgkmcnt(0)
	s_barrier
	s_setprio 1
	s_waitcnt lgkmcnt(0)
	v_mfma_f32_16x16x32_bf16 v[62:65], v[134:137], v[204:207], v[62:65]
	v_mfma_f32_16x16x32_bf16 v[58:61], v[166:169], v[204:207], v[58:61]
	v_mfma_f32_16x16x32_bf16 v[54:57], v[134:137], v[212:215], v[54:57]
	v_mfma_f32_16x16x32_bf16 v[50:53], v[166:169], v[212:215], v[50:53]
	v_mfma_f32_16x16x32_bf16 v[46:49], v[134:137], v[220:223], v[46:49]
	v_mfma_f32_16x16x32_bf16 v[42:45], v[166:169], v[220:223], v[42:45]
	v_mfma_f32_16x16x32_bf16 v[38:41], v[134:137], v[228:231], v[38:41]
	v_mfma_f32_16x16x32_bf16 v[34:37], v[166:169], v[228:231], v[34:37]
	v_mfma_f32_16x16x32_bf16 v[62:65], v[162:165], v[208:211], v[62:65]
	v_mfma_f32_16x16x32_bf16 v[58:61], v[184:187], v[208:211], v[58:61]
	v_mfma_f32_16x16x32_bf16 v[54:57], v[162:165], v[216:219], v[54:57]
	v_mfma_f32_16x16x32_bf16 v[50:53], v[184:187], v[216:219], v[50:53]
	v_mfma_f32_16x16x32_bf16 v[46:49], v[162:165], v[224:227], v[46:49]
	v_mfma_f32_16x16x32_bf16 v[42:45], v[184:187], v[224:227], v[42:45]
	v_mfma_f32_16x16x32_bf16 v[38:41], v[162:165], v[232:235], v[38:41]
	v_mfma_f32_16x16x32_bf16 v[34:37], v[184:187], v[232:235], v[34:37]
	v_mfma_f32_16x16x32_bf16 v[30:33], v[188:191], v[204:207], v[30:33]
	v_mfma_f32_16x16x32_bf16 v[26:29], v[196:199], v[204:207], v[26:29]
	v_mfma_f32_16x16x32_bf16 v[22:25], v[188:191], v[212:215], v[22:25]
	v_mfma_f32_16x16x32_bf16 v[18:21], v[196:199], v[212:215], v[18:21]
	v_mfma_f32_16x16x32_bf16 v[14:17], v[188:191], v[220:223], v[14:17]
	v_mfma_f32_16x16x32_bf16 v[10:13], v[196:199], v[220:223], v[10:13]
	v_mfma_f32_16x16x32_bf16 v[6:9], v[188:191], v[228:231], v[6:9]
	v_mfma_f32_16x16x32_bf16 v[2:5], v[196:199], v[228:231], v[2:5]
	v_mfma_f32_16x16x32_bf16 v[30:33], v[192:195], v[208:211], v[30:33]
	v_mfma_f32_16x16x32_bf16 v[26:29], v[200:203], v[208:211], v[26:29]
	v_mfma_f32_16x16x32_bf16 v[22:25], v[192:195], v[216:219], v[22:25]
	v_mfma_f32_16x16x32_bf16 v[18:21], v[200:203], v[216:219], v[18:21]
	v_mfma_f32_16x16x32_bf16 v[14:17], v[192:195], v[224:227], v[14:17]
	v_mfma_f32_16x16x32_bf16 v[10:13], v[200:203], v[224:227], v[10:13]
	v_mfma_f32_16x16x32_bf16 v[6:9], v[192:195], v[232:235], v[6:9]
	v_mfma_f32_16x16x32_bf16 v[2:5], v[200:203], v[232:235], v[2:5]
	s_setprio 0
	s_barrier
	s_add_i32 s65, 0, 0x18000
	v_add_u32_e32 v146, s65, v172
	s_add_i32 s66, 0, 0x1c000
	ds_read_b128 v[134:137], v146
	ds_read_b128 v[162:165], v146 offset:1024
	ds_read_b128 v[166:169], v146 offset:2048
	ds_read_b128 v[184:187], v146 offset:3072
	v_add_u32_e32 v146, s66, v172
	ds_read_b128 v[188:191], v146
	ds_read_b128 v[192:195], v146 offset:1024
	ds_read_b128 v[196:199], v146 offset:2048
	ds_read_b128 v[200:203], v146 offset:3072
	s_add_u32 s38, s38, 0x40000
	s_addc_u32 s39, s39, 0
	s_mov_b32 m0, s34
	v_lshl_add_u64 v[244:245], s[38:39], 0, v[142:143]
	ds_read_b128 v[204:207], v173 offset:32768
	ds_read_b128 v[208:211], v173 offset:33792
	ds_read_b128 v[212:215], v173 offset:34816
	ds_read_b128 v[216:219], v173 offset:35840
	ds_read_b128 v[220:223], v173 offset:36864
	ds_read_b128 v[224:227], v173 offset:37888
	ds_read_b128 v[228:231], v173 offset:38912
	ds_read_b128 v[232:235], v173 offset:39936
	global_load_lds_dwordx4 v[244:245], off
	v_lshl_add_u64 v[244:245], s[38:39], 0, v[144:145]
	s_mov_b32 m0, s35
	s_nop 0
	global_load_lds_dwordx4 v[244:245], off
	s_waitcnt vmcnt(8)
	s_waitcnt lgkmcnt(0)
	s_barrier
	s_setprio 1
	s_waitcnt lgkmcnt(0)
	v_mfma_f32_16x16x32_bf16 v[126:129], v[134:137], v[204:207], v[126:129]
	v_mfma_f32_16x16x32_bf16 v[122:125], v[166:169], v[204:207], v[122:125]
	v_mfma_f32_16x16x32_bf16 v[118:121], v[134:137], v[212:215], v[118:121]
	v_mfma_f32_16x16x32_bf16 v[114:117], v[166:169], v[212:215], v[114:117]
	v_mfma_f32_16x16x32_bf16 v[110:113], v[134:137], v[220:223], v[110:113]
	v_mfma_f32_16x16x32_bf16 v[106:109], v[166:169], v[220:223], v[106:109]
	v_mfma_f32_16x16x32_bf16 v[102:105], v[134:137], v[228:231], v[102:105]
	v_mfma_f32_16x16x32_bf16 v[98:101], v[166:169], v[228:231], v[98:101]
	v_mfma_f32_16x16x32_bf16 v[126:129], v[162:165], v[208:211], v[126:129]
	v_mfma_f32_16x16x32_bf16 v[122:125], v[184:187], v[208:211], v[122:125]
	v_mfma_f32_16x16x32_bf16 v[118:121], v[162:165], v[216:219], v[118:121]
	v_mfma_f32_16x16x32_bf16 v[114:117], v[184:187], v[216:219], v[114:117]
	v_mfma_f32_16x16x32_bf16 v[110:113], v[162:165], v[224:227], v[110:113]
	v_mfma_f32_16x16x32_bf16 v[106:109], v[184:187], v[224:227], v[106:109]
	v_mfma_f32_16x16x32_bf16 v[102:105], v[162:165], v[232:235], v[102:105]
	v_mfma_f32_16x16x32_bf16 v[98:101], v[184:187], v[232:235], v[98:101]
	v_mfma_f32_16x16x32_bf16 v[94:97], v[188:191], v[204:207], v[94:97]
	v_mfma_f32_16x16x32_bf16 v[90:93], v[196:199], v[204:207], v[90:93]
	v_mfma_f32_16x16x32_bf16 v[86:89], v[188:191], v[212:215], v[86:89]
	v_mfma_f32_16x16x32_bf16 v[82:85], v[196:199], v[212:215], v[82:85]
	v_mfma_f32_16x16x32_bf16 v[78:81], v[188:191], v[220:223], v[78:81]
	v_mfma_f32_16x16x32_bf16 v[74:77], v[196:199], v[220:223], v[74:77]
	v_mfma_f32_16x16x32_bf16 v[70:73], v[188:191], v[228:231], v[70:73]
	v_mfma_f32_16x16x32_bf16 v[66:69], v[196:199], v[228:231], v[66:69]
	v_mfma_f32_16x16x32_bf16 v[94:97], v[192:195], v[208:211], v[94:97]
	v_mfma_f32_16x16x32_bf16 v[90:93], v[200:203], v[208:211], v[90:93]
	v_mfma_f32_16x16x32_bf16 v[86:89], v[192:195], v[216:219], v[86:89]
	v_mfma_f32_16x16x32_bf16 v[82:85], v[200:203], v[216:219], v[82:85]
	v_mfma_f32_16x16x32_bf16 v[78:81], v[192:195], v[224:227], v[78:81]
	v_mfma_f32_16x16x32_bf16 v[74:77], v[200:203], v[224:227], v[74:77]
	v_mfma_f32_16x16x32_bf16 v[70:73], v[192:195], v[232:235], v[70:73]
	v_mfma_f32_16x16x32_bf16 v[66:69], v[200:203], v[232:235], v[66:69]
	s_setprio 0
	s_barrier
	s_add_i32 s38, s65, s18
	v_lshl_add_u64 v[236:237], v[236:237], 0, s[40:41]
	s_mov_b32 m0, s38
	ds_read_b128 v[204:207], v173 offset:49152
	ds_read_b128 v[208:211], v173 offset:50176
	ds_read_b128 v[212:215], v173 offset:51200
	ds_read_b128 v[216:219], v173 offset:52224
	ds_read_b128 v[220:223], v173 offset:53248
	ds_read_b128 v[224:227], v173 offset:54272
	ds_read_b128 v[228:231], v173 offset:55296
	ds_read_b128 v[232:235], v173 offset:56320
	global_load_lds_dwordx4 v[236:237], off
	s_add_i32 m0, s38, 0x2000
	s_add_u32 s36, s36, 0x40080
	v_lshl_add_u64 v[236:237], v[238:239], 0, s[40:41]
	s_addc_u32 s37, s37, 0
	s_add_i32 s38, s66, s18
	global_load_lds_dwordx4 v[236:237], off
	v_lshl_add_u64 v[236:237], s[36:37], 0, v[138:139]
	s_mov_b32 m0, s38
	s_nop 0
	global_load_lds_dwordx4 v[236:237], off
	v_lshl_add_u64 v[236:237], s[36:37], 0, v[140:141]
	s_add_i32 m0, s38, 0x2000
	s_nop 0
	global_load_lds_dwordx4 v[236:237], off
	v_lshl_add_u64 v[236:237], v[240:241], 0, s[40:41]
	s_mov_b32 m0, s55
	s_nop 0
	global_load_lds_dwordx4 v[236:237], off
	v_lshl_add_u64 v[236:237], v[242:243], 0, s[40:41]
	s_mov_b32 m0, s56
	s_nop 0
	global_load_lds_dwordx4 v[236:237], off
	s_waitcnt vmcnt(8)
	s_waitcnt lgkmcnt(0)
	s_barrier
	s_setprio 1
	s_waitcnt lgkmcnt(0)
	v_mfma_f32_16x16x32_bf16 v[62:65], v[134:137], v[204:207], v[62:65]
	v_mfma_f32_16x16x32_bf16 v[58:61], v[166:169], v[204:207], v[58:61]
	v_mfma_f32_16x16x32_bf16 v[54:57], v[134:137], v[212:215], v[54:57]
	v_mfma_f32_16x16x32_bf16 v[50:53], v[166:169], v[212:215], v[50:53]
	v_mfma_f32_16x16x32_bf16 v[46:49], v[134:137], v[220:223], v[46:49]
	v_mfma_f32_16x16x32_bf16 v[42:45], v[166:169], v[220:223], v[42:45]
	v_mfma_f32_16x16x32_bf16 v[38:41], v[134:137], v[228:231], v[38:41]
	v_mfma_f32_16x16x32_bf16 v[34:37], v[166:169], v[228:231], v[34:37]
	v_mfma_f32_16x16x32_bf16 v[62:65], v[162:165], v[208:211], v[62:65]
	v_mfma_f32_16x16x32_bf16 v[58:61], v[184:187], v[208:211], v[58:61]
	v_mfma_f32_16x16x32_bf16 v[54:57], v[162:165], v[216:219], v[54:57]
	v_mfma_f32_16x16x32_bf16 v[50:53], v[184:187], v[216:219], v[50:53]
	v_mfma_f32_16x16x32_bf16 v[46:49], v[162:165], v[224:227], v[46:49]
	v_mfma_f32_16x16x32_bf16 v[42:45], v[184:187], v[224:227], v[42:45]
	v_mfma_f32_16x16x32_bf16 v[38:41], v[162:165], v[232:235], v[38:41]
	v_mfma_f32_16x16x32_bf16 v[34:37], v[184:187], v[232:235], v[34:37]
	v_mfma_f32_16x16x32_bf16 v[30:33], v[188:191], v[204:207], v[30:33]
	v_mfma_f32_16x16x32_bf16 v[26:29], v[196:199], v[204:207], v[26:29]
	v_mfma_f32_16x16x32_bf16 v[22:25], v[188:191], v[212:215], v[22:25]
	v_mfma_f32_16x16x32_bf16 v[18:21], v[196:199], v[212:215], v[18:21]
	v_mfma_f32_16x16x32_bf16 v[14:17], v[188:191], v[220:223], v[14:17]
	v_mfma_f32_16x16x32_bf16 v[10:13], v[196:199], v[220:223], v[10:13]
	v_mfma_f32_16x16x32_bf16 v[6:9], v[188:191], v[228:231], v[6:9]
	v_mfma_f32_16x16x32_bf16 v[2:5], v[196:199], v[228:231], v[2:5]
	v_mfma_f32_16x16x32_bf16 v[30:33], v[192:195], v[208:211], v[30:33]
	v_mfma_f32_16x16x32_bf16 v[26:29], v[200:203], v[208:211], v[26:29]
	v_mfma_f32_16x16x32_bf16 v[22:25], v[192:195], v[216:219], v[22:25]
	v_mfma_f32_16x16x32_bf16 v[18:21], v[200:203], v[216:219], v[18:21]
	v_mfma_f32_16x16x32_bf16 v[14:17], v[192:195], v[224:227], v[14:17]
	v_mfma_f32_16x16x32_bf16 v[10:13], v[200:203], v[224:227], v[10:13]
	v_mfma_f32_16x16x32_bf16 v[6:9], v[192:195], v[232:235], v[6:9]
	v_mfma_f32_16x16x32_bf16 v[2:5], v[200:203], v[232:235], v[2:5]
	s_setprio 0
	s_barrier
	s_add_i32 s64, s64, 2
	s_add_u32 s8, s8, 0x100
	s_addc_u32 s9, s9, 0
	s_cmp_gt_u32 s64, 13
	s_cbranch_scc0 .LBB0_108
	s_and_b64 vcc, exec, s[42:43]
	s_cbranch_vccz .LBB0_111
	s_barrier

.LBB0_395:
	v_add_u32_e32 v164, s43, v150
	v_add_u32_e32 v180, s44, v150
	s_add_u32 s36, s10, s30
	ds_read_b128 v[152:155], v164
	ds_read_b128 v[156:159], v164 offset:1024
	ds_read_b128 v[160:163], v164 offset:2048
	ds_read_b128 v[164:167], v164 offset:3072
	ds_read_b128 v[168:171], v180
	ds_read_b128 v[172:175], v180 offset:1024
	ds_read_b128 v[176:179], v180 offset:2048
	ds_read_b128 v[180:183], v180 offset:3072
	s_addc_u32 s37, s11, s31
	s_add_u32 s36, s36, 0x100
	s_addc_u32 s37, s37, 0
	s_add_u32 s50, s25, s30
	s_addc_u32 s51, s48, s31
	s_cmpk_eq_i32 s30, 0x700
	s_cselect_b32 s39, s29, s37
	s_cselect_b32 s38, s28, s36
	s_cselect_b32 s37, s27, s51
	s_cselect_b32 s36, s26, s50
	v_lshl_add_u64 v[192:193], v[146:147], 0, s[30:31]
	s_add_i32 m0, s20, 0xc000
	ds_read_b128 v[184:187], v151
	ds_read_b128 v[188:191], v151 offset:1024
	ds_read_b128 v[196:199], v151 offset:2048
	ds_read_b128 v[200:203], v151 offset:3072
	ds_read_b128 v[204:207], v151 offset:4096
	ds_read_b128 v[208:211], v151 offset:5120
	ds_read_b128 v[212:215], v151 offset:6144
	ds_read_b128 v[216:219], v151 offset:7168
	global_load_lds_dwordx4 v[192:193], off
	v_lshl_add_u64 v[192:193], v[148:149], 0, s[30:31]
	s_add_i32 m0, s20, 0xe000
	s_nop 0
	global_load_lds_dwordx4 v[192:193], off
	s_waitcnt vmcnt(8)
	s_waitcnt lgkmcnt(0)
	s_barrier
	s_setprio 1
	s_waitcnt lgkmcnt(0)
	v_mfma_f32_16x16x32_bf16 v[126:129], v[152:155], v[184:187], v[126:129]
	v_mfma_f32_16x16x32_bf16 v[122:125], v[160:163], v[184:187], v[122:125]
	v_mfma_f32_16x16x32_bf16 v[118:121], v[152:155], v[196:199], v[118:121]
	v_mfma_f32_16x16x32_bf16 v[114:117], v[160:163], v[196:199], v[114:117]
	v_mfma_f32_16x16x32_bf16 v[110:113], v[152:155], v[204:207], v[110:113]
	v_mfma_f32_16x16x32_bf16 v[102:105], v[160:163], v[204:207], v[102:105]
	v_mfma_f32_16x16x32_bf16 v[94:97], v[152:155], v[212:215], v[94:97]
	v_mfma_f32_16x16x32_bf16 v[86:89], v[160:163], v[212:215], v[86:89]
	v_mfma_f32_16x16x32_bf16 v[126:129], v[156:159], v[188:191], v[126:129]
	v_mfma_f32_16x16x32_bf16 v[122:125], v[164:167], v[188:191], v[122:125]
	v_mfma_f32_16x16x32_bf16 v[118:121], v[156:159], v[200:203], v[118:121]
	v_mfma_f32_16x16x32_bf16 v[114:117], v[164:167], v[200:203], v[114:117]
	v_mfma_f32_16x16x32_bf16 v[110:113], v[156:159], v[208:211], v[110:113]
	v_mfma_f32_16x16x32_bf16 v[102:105], v[164:167], v[208:211], v[102:105]
	v_mfma_f32_16x16x32_bf16 v[94:97], v[156:159], v[216:219], v[94:97]
	v_mfma_f32_16x16x32_bf16 v[86:89], v[164:167], v[216:219], v[86:89]
	v_mfma_f32_16x16x32_bf16 v[106:109], v[168:171], v[184:187], v[106:109]
	v_mfma_f32_16x16x32_bf16 v[98:101], v[176:179], v[184:187], v[98:101]
	v_mfma_f32_16x16x32_bf16 v[90:93], v[168:171], v[196:199], v[90:93]
	v_mfma_f32_16x16x32_bf16 v[82:85], v[176:179], v[196:199], v[82:85]
	v_mfma_f32_16x16x32_bf16 v[78:81], v[168:171], v[204:207], v[78:81]
	v_mfma_f32_16x16x32_bf16 v[74:77], v[176:179], v[204:207], v[74:77]
	v_mfma_f32_16x16x32_bf16 v[70:73], v[168:171], v[212:215], v[70:73]
	v_mfma_f32_16x16x32_bf16 v[66:69], v[176:179], v[212:215], v[66:69]
	v_mfma_f32_16x16x32_bf16 v[106:109], v[172:175], v[188:191], v[106:109]
	v_mfma_f32_16x16x32_bf16 v[98:101], v[180:183], v[188:191], v[98:101]
	v_mfma_f32_16x16x32_bf16 v[90:93], v[172:175], v[200:203], v[90:93]
	v_mfma_f32_16x16x32_bf16 v[82:85], v[180:183], v[200:203], v[82:85]
	v_mfma_f32_16x16x32_bf16 v[78:81], v[172:175], v[208:211], v[78:81]
	v_mfma_f32_16x16x32_bf16 v[74:77], v[180:183], v[208:211], v[74:77]
	v_mfma_f32_16x16x32_bf16 v[70:73], v[172:175], v[216:219], v[70:73]
	v_mfma_f32_16x16x32_bf16 v[66:69], v[180:183], v[216:219], v[66:69]
	s_setprio 0
	s_barrier
	s_add_i32 s50, s43, s15
	v_lshl_add_u64 v[192:193], s[36:37], 0, v[130:131]
	s_mov_b32 m0, s50
	ds_read_b128 v[184:187], v151 offset:16384
	ds_read_b128 v[188:191], v151 offset:17408
	ds_read_b128 v[196:199], v151 offset:18432
	ds_read_b128 v[200:203], v151 offset:19456
	ds_read_b128 v[204:207], v151 offset:20480
	ds_read_b128 v[208:211], v151 offset:21504
	ds_read_b128 v[212:215], v151 offset:22528
	ds_read_b128 v[216:219], v151 offset:23552
	global_load_lds_dwordx4 v[192:193], off
	s_add_i32 m0, s50, 0x2000
	s_add_u32 s50, s36, 0x40000
	v_lshl_add_u64 v[220:221], s[36:37], 0, v[132:133]
	s_addc_u32 s51, s37, 0
	s_add_i32 s53, s44, s15
	global_load_lds_dwordx4 v[220:221], off
	v_lshl_add_u64 v[222:223], s[50:51], 0, v[130:131]
	s_mov_b32 m0, s53
	v_lshl_add_u64 v[224:225], s[38:39], 0, v[136:137]
	global_load_lds_dwordx4 v[222:223], off
	v_lshl_add_u64 v[222:223], s[50:51], 0, v[132:133]
	s_add_i32 m0, s53, 0x2000
	s_nop 0
	global_load_lds_dwordx4 v[222:223], off
	v_lshl_add_u64 v[222:223], s[38:39], 0, v[134:135]
	s_mov_b32 m0, s20
	s_nop 0
	global_load_lds_dwordx4 v[222:223], off
	s_mov_b32 m0, s21
	s_nop 0
	global_load_lds_dwordx4 v[224:225], off
	s_waitcnt vmcnt(8)
	s_waitcnt lgkmcnt(0)
	s_barrier
	s_setprio 1
	s_waitcnt lgkmcnt(0)
	v_mfma_f32_16x16x32_bf16 v[62:65], v[152:155], v[184:187], v[62:65]
	v_mfma_f32_16x16x32_bf16 v[58:61], v[160:163], v[184:187], v[58:61]
	v_mfma_f32_16x16x32_bf16 v[54:57], v[152:155], v[196:199], v[54:57]
	v_mfma_f32_16x16x32_bf16 v[50:53], v[160:163], v[196:199], v[50:53]
	v_mfma_f32_16x16x32_bf16 v[46:49], v[152:155], v[204:207], v[46:49]
	v_mfma_f32_16x16x32_bf16 v[38:41], v[160:163], v[204:207], v[38:41]
	v_mfma_f32_16x16x32_bf16 v[30:33], v[152:155], v[212:215], v[30:33]
	v_mfma_f32_16x16x32_bf16 v[22:25], v[160:163], v[212:215], v[22:25]
	v_mfma_f32_16x16x32_bf16 v[62:65], v[156:159], v[188:191], v[62:65]
	v_mfma_f32_16x16x32_bf16 v[58:61], v[164:167], v[188:191], v[58:61]
	v_mfma_f32_16x16x32_bf16 v[54:57], v[156:159], v[200:203], v[54:57]
	v_mfma_f32_16x16x32_bf16 v[50:53], v[164:167], v[200:203], v[50:53]
	v_mfma_f32_16x16x32_bf16 v[46:49], v[156:159], v[208:211], v[46:49]
	v_mfma_f32_16x16x32_bf16 v[38:41], v[164:167], v[208:211], v[38:41]
	v_mfma_f32_16x16x32_bf16 v[30:33], v[156:159], v[216:219], v[30:33]
	v_mfma_f32_16x16x32_bf16 v[22:25], v[164:167], v[216:219], v[22:25]
	v_mfma_f32_16x16x32_bf16 v[42:45], v[168:171], v[184:187], v[42:45]
	v_mfma_f32_16x16x32_bf16 v[34:37], v[176:179], v[184:187], v[34:37]
	v_mfma_f32_16x16x32_bf16 v[26:29], v[168:171], v[196:199], v[26:29]
	v_mfma_f32_16x16x32_bf16 v[18:21], v[176:179], v[196:199], v[18:21]
	v_mfma_f32_16x16x32_bf16 v[14:17], v[168:171], v[204:207], v[14:17]
	v_mfma_f32_16x16x32_bf16 v[10:13], v[176:179], v[204:207], v[10:13]
	v_mfma_f32_16x16x32_bf16 v[6:9], v[168:171], v[212:215], v[6:9]
	v_mfma_f32_16x16x32_bf16 v[2:5], v[176:179], v[212:215], v[2:5]
	v_mfma_f32_16x16x32_bf16 v[42:45], v[172:175], v[188:191], v[42:45]
	v_mfma_f32_16x16x32_bf16 v[34:37], v[180:183], v[188:191], v[34:37]
	v_mfma_f32_16x16x32_bf16 v[26:29], v[172:175], v[200:203], v[26:29]
	v_mfma_f32_16x16x32_bf16 v[18:21], v[180:183], v[200:203], v[18:21]
	v_mfma_f32_16x16x32_bf16 v[14:17], v[172:175], v[208:211], v[14:17]
	v_mfma_f32_16x16x32_bf16 v[10:13], v[180:183], v[208:211], v[10:13]
	v_mfma_f32_16x16x32_bf16 v[6:9], v[172:175], v[216:219], v[6:9]
	v_mfma_f32_16x16x32_bf16 v[2:5], v[180:183], v[216:219], v[2:5]
	s_setprio 0
	s_barrier
	s_add_i32 s50, 0, 0x18000
	s_add_i32 s51, 0, 0x1c000
	v_add_u32_e32 v164, s50, v150
	v_add_u32_e32 v180, s51, v150
	ds_read_b128 v[152:155], v164
	ds_read_b128 v[156:159], v164 offset:1024
	ds_read_b128 v[160:163], v164 offset:2048
	ds_read_b128 v[164:167], v164 offset:3072
	ds_read_b128 v[168:171], v180
	ds_read_b128 v[172:175], v180 offset:1024
	ds_read_b128 v[176:179], v180 offset:2048
	ds_read_b128 v[180:183], v180 offset:3072
	s_add_u32 s38, s38, 0x40000
	s_addc_u32 s39, s39, 0
	s_mov_b32 m0, s34
	v_lshl_add_u64 v[226:227], s[38:39], 0, v[134:135]
	ds_read_b128 v[184:187], v151 offset:32768
	ds_read_b128 v[188:191], v151 offset:33792
	ds_read_b128 v[196:199], v151 offset:34816
	ds_read_b128 v[200:203], v151 offset:35840
	ds_read_b128 v[204:207], v151 offset:36864
	ds_read_b128 v[208:211], v151 offset:37888
	ds_read_b128 v[212:215], v151 offset:38912
	ds_read_b128 v[216:219], v151 offset:39936
	global_load_lds_dwordx4 v[226:227], off
	v_lshl_add_u64 v[226:227], s[38:39], 0, v[136:137]
	s_mov_b32 m0, s35
	s_nop 0
	global_load_lds_dwordx4 v[226:227], off
	s_waitcnt vmcnt(8)
	s_waitcnt lgkmcnt(0)
	s_barrier
	s_setprio 1
	s_waitcnt lgkmcnt(0)
	v_mfma_f32_16x16x32_bf16 v[126:129], v[152:155], v[184:187], v[126:129]
	v_mfma_f32_16x16x32_bf16 v[122:125], v[160:163], v[184:187], v[122:125]
	v_mfma_f32_16x16x32_bf16 v[118:121], v[152:155], v[196:199], v[118:121]
	v_mfma_f32_16x16x32_bf16 v[114:117], v[160:163], v[196:199], v[114:117]
	v_mfma_f32_16x16x32_bf16 v[110:113], v[152:155], v[204:207], v[110:113]
	v_mfma_f32_16x16x32_bf16 v[102:105], v[160:163], v[204:207], v[102:105]
	v_mfma_f32_16x16x32_bf16 v[94:97], v[152:155], v[212:215], v[94:97]
	v_mfma_f32_16x16x32_bf16 v[86:89], v[160:163], v[212:215], v[86:89]
	v_mfma_f32_16x16x32_bf16 v[126:129], v[156:159], v[188:191], v[126:129]
	v_mfma_f32_16x16x32_bf16 v[122:125], v[164:167], v[188:191], v[122:125]
	v_mfma_f32_16x16x32_bf16 v[118:121], v[156:159], v[200:203], v[118:121]
	v_mfma_f32_16x16x32_bf16 v[114:117], v[164:167], v[200:203], v[114:117]
	v_mfma_f32_16x16x32_bf16 v[110:113], v[156:159], v[208:211], v[110:113]
	v_mfma_f32_16x16x32_bf16 v[102:105], v[164:167], v[208:211], v[102:105]
	v_mfma_f32_16x16x32_bf16 v[94:97], v[156:159], v[216:219], v[94:97]
	v_mfma_f32_16x16x32_bf16 v[86:89], v[164:167], v[216:219], v[86:89]
	v_mfma_f32_16x16x32_bf16 v[106:109], v[168:171], v[184:187], v[106:109]
	v_mfma_f32_16x16x32_bf16 v[98:101], v[176:179], v[184:187], v[98:101]
	v_mfma_f32_16x16x32_bf16 v[90:93], v[168:171], v[196:199], v[90:93]
	v_mfma_f32_16x16x32_bf16 v[82:85], v[176:179], v[196:199], v[82:85]
	v_mfma_f32_16x16x32_bf16 v[78:81], v[168:171], v[204:207], v[78:81]
	v_mfma_f32_16x16x32_bf16 v[74:77], v[176:179], v[204:207], v[74:77]
	v_mfma_f32_16x16x32_bf16 v[70:73], v[168:171], v[212:215], v[70:73]
	v_mfma_f32_16x16x32_bf16 v[66:69], v[176:179], v[212:215], v[66:69]
	v_mfma_f32_16x16x32_bf16 v[106:109], v[172:175], v[188:191], v[106:109]
	v_mfma_f32_16x16x32_bf16 v[98:101], v[180:183], v[188:191], v[98:101]
	v_mfma_f32_16x16x32_bf16 v[90:93], v[172:175], v[200:203], v[90:93]
	v_mfma_f32_16x16x32_bf16 v[82:85], v[180:183], v[200:203], v[82:85]
	v_mfma_f32_16x16x32_bf16 v[78:81], v[172:175], v[208:211], v[78:81]
	v_mfma_f32_16x16x32_bf16 v[74:77], v[180:183], v[208:211], v[74:77]
	v_mfma_f32_16x16x32_bf16 v[70:73], v[172:175], v[216:219], v[70:73]
	v_mfma_f32_16x16x32_bf16 v[66:69], v[180:183], v[216:219], v[66:69]
	s_setprio 0
	s_barrier
	s_add_i32 s38, s50, s15
	v_lshl_add_u64 v[192:193], v[192:193], 0, s[22:23]
	s_mov_b32 m0, s38
	ds_read_b128 v[184:187], v151 offset:49152
	ds_read_b128 v[188:191], v151 offset:50176
	ds_read_b128 v[196:199], v151 offset:51200
	ds_read_b128 v[200:203], v151 offset:52224
	ds_read_b128 v[204:207], v151 offset:53248
	ds_read_b128 v[208:211], v151 offset:54272
	ds_read_b128 v[212:215], v151 offset:55296
	ds_read_b128 v[216:219], v151 offset:56320
	global_load_lds_dwordx4 v[192:193], off
	s_add_i32 m0, s38, 0x2000
	s_add_u32 s36, s36, 0x40080
	v_lshl_add_u64 v[192:193], v[220:221], 0, s[22:23]
	s_addc_u32 s37, s37, 0
	s_add_i32 s38, s51, s15
	global_load_lds_dwordx4 v[192:193], off
	v_lshl_add_u64 v[192:193], s[36:37], 0, v[130:131]
	s_mov_b32 m0, s38
	s_nop 0
	global_load_lds_dwordx4 v[192:193], off
	v_lshl_add_u64 v[192:193], s[36:37], 0, v[132:133]
	s_add_i32 m0, s38, 0x2000
	s_nop 0
	global_load_lds_dwordx4 v[192:193], off
	v_lshl_add_u64 v[192:193], v[222:223], 0, s[22:23]
	s_mov_b32 m0, s41
	s_nop 0
	global_load_lds_dwordx4 v[192:193], off
	v_lshl_add_u64 v[192:193], v[224:225], 0, s[22:23]
	s_mov_b32 m0, s42
	s_nop 0
	global_load_lds_dwordx4 v[192:193], off
	s_waitcnt vmcnt(8)
	s_waitcnt lgkmcnt(0)
	s_barrier
	s_setprio 1
	s_waitcnt lgkmcnt(0)
	v_mfma_f32_16x16x32_bf16 v[62:65], v[152:155], v[184:187], v[62:65]
	v_mfma_f32_16x16x32_bf16 v[58:61], v[160:163], v[184:187], v[58:61]
	v_mfma_f32_16x16x32_bf16 v[54:57], v[152:155], v[196:199], v[54:57]
	v_mfma_f32_16x16x32_bf16 v[50:53], v[160:163], v[196:199], v[50:53]
	v_mfma_f32_16x16x32_bf16 v[46:49], v[152:155], v[204:207], v[46:49]
	v_mfma_f32_16x16x32_bf16 v[38:41], v[160:163], v[204:207], v[38:41]
	v_mfma_f32_16x16x32_bf16 v[30:33], v[152:155], v[212:215], v[30:33]
	v_mfma_f32_16x16x32_bf16 v[22:25], v[160:163], v[212:215], v[22:25]
	v_mfma_f32_16x16x32_bf16 v[62:65], v[156:159], v[188:191], v[62:65]
	v_mfma_f32_16x16x32_bf16 v[58:61], v[164:167], v[188:191], v[58:61]
	v_mfma_f32_16x16x32_bf16 v[54:57], v[156:159], v[200:203], v[54:57]
	v_mfma_f32_16x16x32_bf16 v[50:53], v[164:167], v[200:203], v[50:53]
	v_mfma_f32_16x16x32_bf16 v[46:49], v[156:159], v[208:211], v[46:49]
	v_mfma_f32_16x16x32_bf16 v[38:41], v[164:167], v[208:211], v[38:41]
	v_mfma_f32_16x16x32_bf16 v[30:33], v[156:159], v[216:219], v[30:33]
	v_mfma_f32_16x16x32_bf16 v[22:25], v[164:167], v[216:219], v[22:25]
	v_mfma_f32_16x16x32_bf16 v[42:45], v[168:171], v[184:187], v[42:45]
	v_mfma_f32_16x16x32_bf16 v[34:37], v[176:179], v[184:187], v[34:37]
	v_mfma_f32_16x16x32_bf16 v[26:29], v[168:171], v[196:199], v[26:29]
	v_mfma_f32_16x16x32_bf16 v[18:21], v[176:179], v[196:199], v[18:21]
	v_mfma_f32_16x16x32_bf16 v[14:17], v[168:171], v[204:207], v[14:17]
	v_mfma_f32_16x16x32_bf16 v[10:13], v[176:179], v[204:207], v[10:13]
	v_mfma_f32_16x16x32_bf16 v[6:9], v[168:171], v[212:215], v[6:9]
	v_mfma_f32_16x16x32_bf16 v[2:5], v[176:179], v[212:215], v[2:5]
	v_mfma_f32_16x16x32_bf16 v[42:45], v[172:175], v[188:191], v[42:45]
	v_mfma_f32_16x16x32_bf16 v[34:37], v[180:183], v[188:191], v[34:37]
	v_mfma_f32_16x16x32_bf16 v[26:29], v[172:175], v[200:203], v[26:29]
	v_mfma_f32_16x16x32_bf16 v[18:21], v[180:183], v[200:203], v[18:21]
	v_mfma_f32_16x16x32_bf16 v[14:17], v[172:175], v[208:211], v[14:17]
	v_mfma_f32_16x16x32_bf16 v[10:13], v[180:183], v[208:211], v[10:13]
	v_mfma_f32_16x16x32_bf16 v[6:9], v[172:175], v[216:219], v[6:9]
	v_mfma_f32_16x16x32_bf16 v[2:5], v[180:183], v[216:219], v[2:5]
	s_setprio 0
	s_barrier
	s_add_i32 s49, s49, 2
	s_add_u32 s30, s30, 0x100
	s_addc_u32 s31, s31, 0
	s_cmp_gt_u32 s49, 13
	s_cbranch_scc0 .LBB0_395
	s_add_u32 s30, s25, 0xffffff00
	s_addc_u32 s31, s48, -1
	s_andn2_b64 vcc, exec, s[6:7]
	s_cbranch_vccnz .LBB0_386
	v_mov_b32_e32 v2, 0
	s_mov_b32 s8, s45
	s_mov_b32 s0, s24
	s_mov_b64 s[10:11], s[28:29]
	s_mov_b32 s40, s47
	v_mov_b32_e32 v3, v2
	v_mov_b32_e32 v4, v2
	v_mov_b32_e32 v5, v2
	v_mov_b32_e32 v6, v2
	v_mov_b32_e32 v7, v2
	v_mov_b32_e32 v8, v2
	v_mov_b32_e32 v9, v2
	v_mov_b32_e32 v10, v2
	v_mov_b32_e32 v11, v2
	v_mov_b32_e32 v12, v2
	v_mov_b32_e32 v13, v2
	v_mov_b32_e32 v14, v2
	v_mov_b32_e32 v15, v2
	v_mov_b32_e32 v16, v2
	v_mov_b32_e32 v17, v2
	v_mov_b32_e32 v18, v2
	v_mov_b32_e32 v19, v2
	v_mov_b32_e32 v20, v2
	v_mov_b32_e32 v21, v2
	v_mov_b32_e32 v26, v2
	v_mov_b32_e32 v27, v2
	v_mov_b32_e32 v28, v2
	v_mov_b32_e32 v29, v2
	v_mov_b32_e32 v34, v2
	v_mov_b32_e32 v35, v2
	v_mov_b32_e32 v36, v2
	v_mov_b32_e32 v37, v2
	v_mov_b32_e32 v42, v2
	v_mov_b32_e32 v43, v2
	v_mov_b32_e32 v44, v2
	v_mov_b32_e32 v45, v2
	v_mov_b32_e32 v22, v2
	v_mov_b32_e32 v23, v2
	v_mov_b32_e32 v24, v2
	v_mov_b32_e32 v25, v2
	v_mov_b32_e32 v30, v2
	v_mov_b32_e32 v31, v2
	v_mov_b32_e32 v32, v2
	v_mov_b32_e32 v33, v2
	v_mov_b32_e32 v38, v2
	v_mov_b32_e32 v39, v2
	v_mov_b32_e32 v40, v2
	v_mov_b32_e32 v41, v2
	v_mov_b32_e32 v46, v2
	v_mov_b32_e32 v47, v2
	v_mov_b32_e32 v48, v2
	v_mov_b32_e32 v49, v2
	v_mov_b32_e32 v50, v2
	v_mov_b32_e32 v51, v2
	v_mov_b32_e32 v52, v2
	v_mov_b32_e32 v53, v2
	v_mov_b32_e32 v54, v2
	v_mov_b32_e32 v55, v2
	v_mov_b32_e32 v56, v2
	v_mov_b32_e32 v57, v2
	v_mov_b32_e32 v58, v2
	v_mov_b32_e32 v59, v2
	v_mov_b32_e32 v60, v2
	v_mov_b32_e32 v61, v2
	v_mov_b32_e32 v62, v2
	v_mov_b32_e32 v63, v2
	v_mov_b32_e32 v64, v2
	v_mov_b32_e32 v65, v2
	v_mov_b32_e32 v66, v2
	v_mov_b32_e32 v67, v2
	v_mov_b32_e32 v68, v2
	v_mov_b32_e32 v69, v2
	v_mov_b32_e32 v70, v2
	v_mov_b32_e32 v71, v2
	v_mov_b32_e32 v72, v2
	v_mov_b32_e32 v73, v2
	v_mov_b32_e32 v74, v2
	v_mov_b32_e32 v75, v2
	v_mov_b32_e32 v76, v2
	v_mov_b32_e32 v77, v2
	v_mov_b32_e32 v78, v2
	v_mov_b32_e32 v79, v2
	v_mov_b32_e32 v80, v2
	v_mov_b32_e32 v81, v2
	v_mov_b32_e32 v82, v2
	v_mov_b32_e32 v83, v2
	v_mov_b32_e32 v84, v2
	v_mov_b32_e32 v85, v2
	v_mov_b32_e32 v90, v2
	v_mov_b32_e32 v91, v2
	v_mov_b32_e32 v92, v2
	v_mov_b32_e32 v93, v2
	v_mov_b32_e32 v98, v2
	v_mov_b32_e32 v99, v2
	v_mov_b32_e32 v100, v2
	v_mov_b32_e32 v101, v2
	v_mov_b32_e32 v106, v2
	v_mov_b32_e32 v107, v2
	v_mov_b32_e32 v108, v2
	v_mov_b32_e32 v109, v2
	v_mov_b32_e32 v86, v2
	v_mov_b32_e32 v87, v2
	v_mov_b32_e32 v88, v2
	v_mov_b32_e32 v89, v2
	v_mov_b32_e32 v94, v2
	v_mov_b32_e32 v95, v2
	v_mov_b32_e32 v96, v2
	v_mov_b32_e32 v97, v2
	v_mov_b32_e32 v102, v2
	v_mov_b32_e32 v103, v2
	v_mov_b32_e32 v104, v2
	v_mov_b32_e32 v105, v2
	v_mov_b32_e32 v110, v2
	v_mov_b32_e32 v111, v2
	v_mov_b32_e32 v112, v2
	v_mov_b32_e32 v113, v2
	v_mov_b32_e32 v114, v2
	v_mov_b32_e32 v115, v2
	v_mov_b32_e32 v116, v2
	v_mov_b32_e32 v117, v2
	v_mov_b32_e32 v118, v2
	v_mov_b32_e32 v119, v2
	v_mov_b32_e32 v120, v2
	v_mov_b32_e32 v121, v2
	v_mov_b32_e32 v122, v2
	v_mov_b32_e32 v123, v2
	v_mov_b32_e32 v124, v2
	v_mov_b32_e32 v125, v2
	v_mov_b32_e32 v126, v2
	v_mov_b32_e32 v127, v2
	v_mov_b32_e32 v128, v2
	v_mov_b32_e32 v129, v2
	s_andn2_b64 vcc, exec, s[4:5]
	s_cbranch_vccnz .LBB0_387

.LBB0_590:
	s_add_u32 vcc_lo, s68, s8
	s_addc_u32 vcc_hi, s69, s9
	s_add_u32 vcc_lo, vcc_lo, 0x100
	s_addc_u32 vcc_hi, vcc_hi, 0
	s_and_b64 s[38:39], exec, s[38:39]
	s_cselect_b32 s39, s89, vcc_hi
	s_cselect_b32 s38, s88, vcc_lo
	s_add_i32 s43, 0, 0x10000
	v_add_u32_e32 v168, s43, v179
	s_add_i32 s41, 0, 0x14000
	ds_read_b128 v[160:163], v168
	ds_read_b128 v[164:167], v168 offset:1024
	ds_read_b128 v[186:189], v168 offset:2048
	ds_read_b128 v[190:193], v168 offset:3072
	v_add_u32_e32 v168, s41, v179
	ds_read_b128 v[194:197], v168
	ds_read_b128 v[198:201], v168 offset:1024
	ds_read_b128 v[202:205], v168 offset:2048
	ds_read_b128 v[206:209], v168 offset:3072
	v_lshl_add_u64 v[168:169], v[148:149], 0, s[8:9]
	s_add_i32 m0, s51, 0xc000
	ds_read_b128 v[210:213], v185
	ds_read_b128 v[214:217], v185 offset:1024
	ds_read_b128 v[218:221], v185 offset:2048
	ds_read_b128 v[222:225], v185 offset:3072
	ds_read_b128 v[226:229], v185 offset:4096
	ds_read_b128 v[232:235], v185 offset:5120
	ds_read_b128 v[236:239], v185 offset:6144
	ds_read_b128 v[240:243], v185 offset:7168
	global_load_lds_dwordx4 v[168:169], off
	v_lshl_add_u64 v[168:169], v[146:147], 0, s[8:9]
	s_add_i32 m0, s51, 0xe000
	s_nop 0
	global_load_lds_dwordx4 v[168:169], off
	s_waitcnt vmcnt(8)
	s_waitcnt lgkmcnt(0)
	s_barrier
	s_setprio 1
	s_waitcnt lgkmcnt(0)
	v_mfma_f32_16x16x32_bf16 v[134:137], v[160:163], v[210:213], v[134:137]
	v_mfma_f32_16x16x32_bf16 v[130:133], v[186:189], v[210:213], v[130:133]
	v_mfma_f32_16x16x32_bf16 v[126:129], v[160:163], v[218:221], v[126:129]
	v_mfma_f32_16x16x32_bf16 v[122:125], v[186:189], v[218:221], v[122:125]
	v_mfma_f32_16x16x32_bf16 v[118:121], v[160:163], v[226:229], v[118:121]
	v_mfma_f32_16x16x32_bf16 v[114:117], v[186:189], v[226:229], v[114:117]
	v_mfma_f32_16x16x32_bf16 v[110:113], v[160:163], v[236:239], v[110:113]
	v_mfma_f32_16x16x32_bf16 v[106:109], v[186:189], v[236:239], v[106:109]
	v_mfma_f32_16x16x32_bf16 v[134:137], v[164:167], v[214:217], v[134:137]
	v_mfma_f32_16x16x32_bf16 v[130:133], v[190:193], v[214:217], v[130:133]
	v_mfma_f32_16x16x32_bf16 v[126:129], v[164:167], v[222:225], v[126:129]
	v_mfma_f32_16x16x32_bf16 v[122:125], v[190:193], v[222:225], v[122:125]
	v_mfma_f32_16x16x32_bf16 v[118:121], v[164:167], v[232:235], v[118:121]
	v_mfma_f32_16x16x32_bf16 v[114:117], v[190:193], v[232:235], v[114:117]
	v_mfma_f32_16x16x32_bf16 v[110:113], v[164:167], v[240:243], v[110:113]
	v_mfma_f32_16x16x32_bf16 v[106:109], v[190:193], v[240:243], v[106:109]
	v_mfma_f32_16x16x32_bf16 v[102:105], v[194:197], v[210:213], v[102:105]
	v_mfma_f32_16x16x32_bf16 v[98:101], v[202:205], v[210:213], v[98:101]
	v_mfma_f32_16x16x32_bf16 v[94:97], v[194:197], v[218:221], v[94:97]
	v_mfma_f32_16x16x32_bf16 v[90:93], v[202:205], v[218:221], v[90:93]
	v_mfma_f32_16x16x32_bf16 v[86:89], v[194:197], v[226:229], v[86:89]
	v_mfma_f32_16x16x32_bf16 v[82:85], v[202:205], v[226:229], v[82:85]
	v_mfma_f32_16x16x32_bf16 v[78:81], v[194:197], v[236:239], v[78:81]
	v_mfma_f32_16x16x32_bf16 v[74:77], v[202:205], v[236:239], v[74:77]
	v_mfma_f32_16x16x32_bf16 v[102:105], v[198:201], v[214:217], v[102:105]
	v_mfma_f32_16x16x32_bf16 v[98:101], v[206:209], v[214:217], v[98:101]
	v_mfma_f32_16x16x32_bf16 v[94:97], v[198:201], v[222:225], v[94:97]
	v_mfma_f32_16x16x32_bf16 v[90:93], v[206:209], v[222:225], v[90:93]
	v_mfma_f32_16x16x32_bf16 v[86:89], v[198:201], v[232:235], v[86:89]
	v_mfma_f32_16x16x32_bf16 v[82:85], v[206:209], v[232:235], v[82:85]
	v_mfma_f32_16x16x32_bf16 v[78:81], v[198:201], v[240:243], v[78:81]
	v_mfma_f32_16x16x32_bf16 v[74:77], v[206:209], v[240:243], v[74:77]
	s_setprio 0
	s_barrier
	s_add_i32 s43, s43, s50
	v_mad_u64_u32 v[168:169], vcc, s87, v3, v[4:5]
	s_mov_b32 m0, s43
	ds_read_b128 v[210:213], v185 offset:16384
	ds_read_b128 v[214:217], v185 offset:17408
	ds_read_b128 v[218:221], v185 offset:18432
	ds_read_b128 v[222:225], v185 offset:19456
	ds_read_b128 v[226:229], v185 offset:20480
	ds_read_b128 v[232:235], v185 offset:21504
	ds_read_b128 v[236:239], v185 offset:22528
	ds_read_b128 v[240:243], v185 offset:23552
	global_load_lds_dwordx4 v168, s[96:97]
	s_add_i32 m0, s43, 0x2000
	s_add_u32 s92, s96, s92
	v_mad_u64_u32 v[246:247], vcc, s87, v155, v[156:157]
	s_addc_u32 s93, s97, s93
	s_add_i32 s41, s41, s50
	global_load_lds_dwordx4 v246, s[96:97]
	s_mov_b32 m0, s41
	v_mov_b32_e32 v169, v2
	v_mov_b32_e32 v247, v2
	global_load_lds_dwordx4 v168, s[92:93]
	s_add_i32 m0, s41, 0x2000
	v_lshl_add_u64 v[244:245], s[96:97], 0, v[168:169]
	v_lshl_add_u64 v[248:249], s[96:97], 0, v[246:247]
	v_lshl_add_u64 v[250:251], s[92:93], 0, v[168:169]
	v_lshl_add_u64 v[168:169], s[92:93], 0, v[246:247]
	global_load_lds_dwordx4 v246, s[92:93]
	v_lshl_add_u64 v[246:247], s[38:39], 0, v[152:153]
	s_mov_b32 m0, s51
	v_lshl_add_u64 v[252:253], s[38:39], 0, v[150:151]
	global_load_lds_dwordx4 v[246:247], off
	s_mov_b32 m0, s73
	s_nop 0
	global_load_lds_dwordx4 v[252:253], off
	s_waitcnt vmcnt(8)
	s_waitcnt lgkmcnt(0)
	s_barrier
	s_setprio 1
	s_waitcnt lgkmcnt(0)
	v_mfma_f32_16x16x32_bf16 v[70:73], v[160:163], v[210:213], v[70:73]
	v_mfma_f32_16x16x32_bf16 v[66:69], v[186:189], v[210:213], v[66:69]
	v_mfma_f32_16x16x32_bf16 v[62:65], v[160:163], v[218:221], v[62:65]
	v_mfma_f32_16x16x32_bf16 v[58:61], v[186:189], v[218:221], v[58:61]
	v_mfma_f32_16x16x32_bf16 v[54:57], v[160:163], v[226:229], v[54:57]
	v_mfma_f32_16x16x32_bf16 v[50:53], v[186:189], v[226:229], v[50:53]
	v_mfma_f32_16x16x32_bf16 v[46:49], v[160:163], v[236:239], v[46:49]
	v_mfma_f32_16x16x32_bf16 v[42:45], v[186:189], v[236:239], v[42:45]
	v_mfma_f32_16x16x32_bf16 v[70:73], v[164:167], v[214:217], v[70:73]
	v_mfma_f32_16x16x32_bf16 v[66:69], v[190:193], v[214:217], v[66:69]
	v_mfma_f32_16x16x32_bf16 v[62:65], v[164:167], v[222:225], v[62:65]
	v_mfma_f32_16x16x32_bf16 v[58:61], v[190:193], v[222:225], v[58:61]
	v_mfma_f32_16x16x32_bf16 v[54:57], v[164:167], v[232:235], v[54:57]
	v_mfma_f32_16x16x32_bf16 v[50:53], v[190:193], v[232:235], v[50:53]
	v_mfma_f32_16x16x32_bf16 v[46:49], v[164:167], v[240:243], v[46:49]
	v_mfma_f32_16x16x32_bf16 v[42:45], v[190:193], v[240:243], v[42:45]
	v_mfma_f32_16x16x32_bf16 v[38:41], v[194:197], v[210:213], v[38:41]
	v_mfma_f32_16x16x32_bf16 v[34:37], v[202:205], v[210:213], v[34:37]
	v_mfma_f32_16x16x32_bf16 v[30:33], v[194:197], v[218:221], v[30:33]
	v_mfma_f32_16x16x32_bf16 v[26:29], v[202:205], v[218:221], v[26:29]
	v_mfma_f32_16x16x32_bf16 v[22:25], v[194:197], v[226:229], v[22:25]
	v_mfma_f32_16x16x32_bf16 v[18:21], v[202:205], v[226:229], v[18:21]
	v_mfma_f32_16x16x32_bf16 v[14:17], v[194:197], v[236:239], v[14:17]
	v_mfma_f32_16x16x32_bf16 v[10:13], v[202:205], v[236:239], v[10:13]
	v_mfma_f32_16x16x32_bf16 v[38:41], v[198:201], v[214:217], v[38:41]
	v_mfma_f32_16x16x32_bf16 v[34:37], v[206:209], v[214:217], v[34:37]
	v_mfma_f32_16x16x32_bf16 v[30:33], v[198:201], v[222:225], v[30:33]
	v_mfma_f32_16x16x32_bf16 v[26:29], v[206:209], v[222:225], v[26:29]
	v_mfma_f32_16x16x32_bf16 v[22:25], v[198:201], v[232:235], v[22:25]
	v_mfma_f32_16x16x32_bf16 v[18:21], v[206:209], v[232:235], v[18:21]
	v_mfma_f32_16x16x32_bf16 v[14:17], v[198:201], v[240:243], v[14:17]
	v_mfma_f32_16x16x32_bf16 v[10:13], v[206:209], v[240:243], v[10:13]
	s_setprio 0
	s_barrier
	s_add_i32 s41, 0, 0x18000
	s_add_i32 s43, 0, 0x1c000
	v_add_u32_e32 v190, s41, v179
	v_add_u32_e32 v206, s43, v179
	ds_read_b128 v[160:163], v190
	ds_read_b128 v[164:167], v190 offset:1024
	ds_read_b128 v[186:189], v190 offset:2048
	ds_read_b128 v[190:193], v190 offset:3072
	ds_read_b128 v[194:197], v206
	ds_read_b128 v[198:201], v206 offset:1024
	ds_read_b128 v[202:205], v206 offset:2048
	ds_read_b128 v[206:209], v206 offset:3072
	s_add_u32 s38, s38, s94
	s_addc_u32 s39, s39, s95
	s_mov_b32 m0, s71
	v_lshl_add_u64 v[152:153], s[38:39], 0, v[152:153]
	ds_read_b128 v[210:213], v185 offset:32768
	ds_read_b128 v[214:217], v185 offset:33792
	ds_read_b128 v[218:221], v185 offset:34816
	ds_read_b128 v[222:225], v185 offset:35840
	ds_read_b128 v[226:229], v185 offset:36864
	ds_read_b128 v[232:235], v185 offset:37888
	ds_read_b128 v[236:239], v185 offset:38912
	ds_read_b128 v[240:243], v185 offset:39936
	global_load_lds_dwordx4 v[152:153], off
	v_lshl_add_u64 v[150:151], s[38:39], 0, v[150:151]
	s_mov_b32 m0, s34
	s_nop 0
	global_load_lds_dwordx4 v[150:151], off
	s_waitcnt vmcnt(8)
	s_waitcnt lgkmcnt(0)
	s_barrier
	s_setprio 1
	s_waitcnt lgkmcnt(0)
	v_mfma_f32_16x16x32_bf16 v[134:137], v[160:163], v[210:213], v[134:137]
	v_mfma_f32_16x16x32_bf16 v[130:133], v[186:189], v[210:213], v[130:133]
	v_mfma_f32_16x16x32_bf16 v[126:129], v[160:163], v[218:221], v[126:129]
	v_mfma_f32_16x16x32_bf16 v[122:125], v[186:189], v[218:221], v[122:125]
	v_mfma_f32_16x16x32_bf16 v[118:121], v[160:163], v[226:229], v[118:121]
	v_mfma_f32_16x16x32_bf16 v[114:117], v[186:189], v[226:229], v[114:117]
	v_mfma_f32_16x16x32_bf16 v[110:113], v[160:163], v[236:239], v[110:113]
	v_mfma_f32_16x16x32_bf16 v[106:109], v[186:189], v[236:239], v[106:109]
	v_mfma_f32_16x16x32_bf16 v[134:137], v[164:167], v[214:217], v[134:137]
	v_mfma_f32_16x16x32_bf16 v[130:133], v[190:193], v[214:217], v[130:133]
	v_mfma_f32_16x16x32_bf16 v[126:129], v[164:167], v[222:225], v[126:129]
	v_mfma_f32_16x16x32_bf16 v[122:125], v[190:193], v[222:225], v[122:125]
	v_mfma_f32_16x16x32_bf16 v[118:121], v[164:167], v[232:235], v[118:121]
	v_mfma_f32_16x16x32_bf16 v[114:117], v[190:193], v[232:235], v[114:117]
	v_mfma_f32_16x16x32_bf16 v[110:113], v[164:167], v[240:243], v[110:113]
	v_mfma_f32_16x16x32_bf16 v[106:109], v[190:193], v[240:243], v[106:109]
	v_mfma_f32_16x16x32_bf16 v[102:105], v[194:197], v[210:213], v[102:105]
	v_mfma_f32_16x16x32_bf16 v[98:101], v[202:205], v[210:213], v[98:101]
	v_mfma_f32_16x16x32_bf16 v[94:97], v[194:197], v[218:221], v[94:97]
	v_mfma_f32_16x16x32_bf16 v[90:93], v[202:205], v[218:221], v[90:93]
	v_mfma_f32_16x16x32_bf16 v[86:89], v[194:197], v[226:229], v[86:89]
	v_mfma_f32_16x16x32_bf16 v[82:85], v[202:205], v[226:229], v[82:85]
	v_mfma_f32_16x16x32_bf16 v[78:81], v[194:197], v[236:239], v[78:81]
	v_mfma_f32_16x16x32_bf16 v[74:77], v[202:205], v[236:239], v[74:77]
	v_mfma_f32_16x16x32_bf16 v[102:105], v[198:201], v[214:217], v[102:105]
	v_mfma_f32_16x16x32_bf16 v[98:101], v[206:209], v[214:217], v[98:101]
	v_mfma_f32_16x16x32_bf16 v[94:97], v[198:201], v[222:225], v[94:97]
	v_mfma_f32_16x16x32_bf16 v[90:93], v[206:209], v[222:225], v[90:93]
	v_mfma_f32_16x16x32_bf16 v[86:89], v[198:201], v[232:235], v[86:89]
	v_mfma_f32_16x16x32_bf16 v[82:85], v[206:209], v[232:235], v[82:85]
	v_mfma_f32_16x16x32_bf16 v[78:81], v[198:201], v[240:243], v[78:81]
	v_mfma_f32_16x16x32_bf16 v[74:77], v[206:209], v[240:243], v[74:77]
	s_setprio 0
	s_barrier
	s_add_i32 s38, s41, s50
	v_lshl_add_u64 v[240:241], v[244:245], 0, s[52:53]
	s_mov_b32 m0, s38
	ds_read_b128 v[150:153], v185 offset:49152
	ds_read_b128 v[210:213], v185 offset:50176
	ds_read_b128 v[214:217], v185 offset:51200
	ds_read_b128 v[218:221], v185 offset:52224
	ds_read_b128 v[222:225], v185 offset:53248
	ds_read_b128 v[226:229], v185 offset:54272
	ds_read_b128 v[232:235], v185 offset:55296
	ds_read_b128 v[236:239], v185 offset:56320
	global_load_lds_dwordx4 v[240:241], off
	v_lshl_add_u64 v[240:241], v[248:249], 0, s[52:53]
	s_add_i32 m0, s38, 0x2000
	s_add_i32 s38, s43, s50
	global_load_lds_dwordx4 v[240:241], off
	v_lshl_add_u64 v[240:241], v[250:251], 0, s[52:53]
	s_mov_b32 m0, s38
	v_lshl_add_u64 v[168:169], v[168:169], 0, s[52:53]
	global_load_lds_dwordx4 v[240:241], off
	s_add_i32 m0, s38, 0x2000
	s_nop 0
	global_load_lds_dwordx4 v[168:169], off
	v_lshl_add_u64 v[168:169], v[246:247], 0, s[52:53]
	s_mov_b32 m0, s23
	s_nop 0
	global_load_lds_dwordx4 v[168:169], off
	v_lshl_add_u64 v[168:169], v[252:253], 0, s[52:53]
	s_mov_b32 m0, s28
	s_nop 0
	global_load_lds_dwordx4 v[168:169], off
	s_waitcnt vmcnt(8)
	s_waitcnt lgkmcnt(0)
	s_barrier
	s_setprio 1
	s_waitcnt lgkmcnt(0)
	v_mfma_f32_16x16x32_bf16 v[70:73], v[160:163], v[150:153], v[70:73]
	v_mfma_f32_16x16x32_bf16 v[66:69], v[186:189], v[150:153], v[66:69]
	v_mfma_f32_16x16x32_bf16 v[62:65], v[160:163], v[214:217], v[62:65]
	v_mfma_f32_16x16x32_bf16 v[58:61], v[186:189], v[214:217], v[58:61]
	v_mfma_f32_16x16x32_bf16 v[54:57], v[160:163], v[222:225], v[54:57]
	v_mfma_f32_16x16x32_bf16 v[50:53], v[186:189], v[222:225], v[50:53]
	v_mfma_f32_16x16x32_bf16 v[46:49], v[160:163], v[232:235], v[46:49]
	v_mfma_f32_16x16x32_bf16 v[42:45], v[186:189], v[232:235], v[42:45]
	v_mfma_f32_16x16x32_bf16 v[70:73], v[164:167], v[210:213], v[70:73]
	v_mfma_f32_16x16x32_bf16 v[66:69], v[190:193], v[210:213], v[66:69]
	v_mfma_f32_16x16x32_bf16 v[62:65], v[164:167], v[218:221], v[62:65]
	v_mfma_f32_16x16x32_bf16 v[58:61], v[190:193], v[218:221], v[58:61]
	v_mfma_f32_16x16x32_bf16 v[54:57], v[164:167], v[226:229], v[54:57]
	v_mfma_f32_16x16x32_bf16 v[50:53], v[190:193], v[226:229], v[50:53]
	v_mfma_f32_16x16x32_bf16 v[46:49], v[164:167], v[236:239], v[46:49]
	v_mfma_f32_16x16x32_bf16 v[42:45], v[190:193], v[236:239], v[42:45]
	v_mfma_f32_16x16x32_bf16 v[38:41], v[194:197], v[150:153], v[38:41]
	v_mfma_f32_16x16x32_bf16 v[34:37], v[202:205], v[150:153], v[34:37]
	v_mfma_f32_16x16x32_bf16 v[30:33], v[194:197], v[214:217], v[30:33]
	v_mfma_f32_16x16x32_bf16 v[26:29], v[202:205], v[214:217], v[26:29]
	v_mfma_f32_16x16x32_bf16 v[22:25], v[194:197], v[222:225], v[22:25]
	v_mfma_f32_16x16x32_bf16 v[18:21], v[202:205], v[222:225], v[18:21]
	v_mfma_f32_16x16x32_bf16 v[14:17], v[194:197], v[232:235], v[14:17]
	v_mfma_f32_16x16x32_bf16 v[10:13], v[202:205], v[232:235], v[10:13]
	v_mfma_f32_16x16x32_bf16 v[38:41], v[198:201], v[210:213], v[38:41]
	v_mfma_f32_16x16x32_bf16 v[34:37], v[206:209], v[210:213], v[34:37]
	v_mfma_f32_16x16x32_bf16 v[30:33], v[198:201], v[218:221], v[30:33]
	v_mfma_f32_16x16x32_bf16 v[26:29], v[206:209], v[218:221], v[26:29]
	v_mfma_f32_16x16x32_bf16 v[22:25], v[198:201], v[226:229], v[22:25]
	v_mfma_f32_16x16x32_bf16 v[18:21], v[206:209], v[226:229], v[18:21]
	v_mfma_f32_16x16x32_bf16 v[14:17], v[198:201], v[236:239], v[14:17]
	v_mfma_f32_16x16x32_bf16 v[10:13], v[206:209], v[236:239], v[10:13]
	s_setprio 0
	s_barrier
	s_add_i32 s63, s63, 2
	s_add_u32 s8, s8, 0x100
	s_addc_u32 s9, s9, 0
	s_cmp_gt_u32 s63, 13
	s_cbranch_scc1 .LBB0_593

.LBB0_946:
	v_add_u32_e32 v164, s88, v150
	v_add_u32_e32 v180, s45, v150
	s_add_u32 s24, s8, s22
	ds_read_b128 v[152:155], v164
	ds_read_b128 v[156:159], v164 offset:1024
	ds_read_b128 v[160:163], v164 offset:2048
	ds_read_b128 v[164:167], v164 offset:3072
	ds_read_b128 v[168:171], v180
	ds_read_b128 v[172:175], v180 offset:1024
	ds_read_b128 v[176:179], v180 offset:2048
	ds_read_b128 v[180:183], v180 offset:3072
	s_addc_u32 s25, s9, s23
	s_add_u32 s24, s24, 0x100
	s_addc_u32 s25, s25, 0
	s_add_u32 s50, s13, s22
	s_addc_u32 s51, s48, s23
	s_cmpk_eq_i32 s22, 0x700
	s_cselect_b32 s27, s21, s25
	s_cselect_b32 s26, s20, s24
	s_cselect_b32 s25, s17, s51
	s_cselect_b32 s24, s16, s50
	v_lshl_add_u64 v[218:219], v[146:147], 0, s[22:23]
	s_add_i32 m0, s37, 0xc000
	ds_read_b128 v[184:187], v151
	ds_read_b128 v[190:193], v151 offset:1024
	ds_read_b128 v[194:197], v151 offset:2048
	ds_read_b128 v[198:201], v151 offset:3072
	ds_read_b128 v[202:205], v151 offset:4096
	ds_read_b128 v[206:209], v151 offset:5120
	ds_read_b128 v[210:213], v151 offset:6144
	ds_read_b128 v[214:217], v151 offset:7168
	global_load_lds_dwordx4 v[218:219], off
	v_lshl_add_u64 v[218:219], v[148:149], 0, s[22:23]
	s_add_i32 m0, s37, 0xe000
	s_nop 0
	global_load_lds_dwordx4 v[218:219], off
	s_waitcnt vmcnt(8)
	s_waitcnt lgkmcnt(0)
	s_barrier
	s_setprio 1
	s_waitcnt lgkmcnt(0)
	v_mfma_f32_16x16x32_bf16 v[126:129], v[152:155], v[184:187], v[126:129]
	v_mfma_f32_16x16x32_bf16 v[122:125], v[160:163], v[184:187], v[122:125]
	v_mfma_f32_16x16x32_bf16 v[110:113], v[152:155], v[194:197], v[110:113]
	v_mfma_f32_16x16x32_bf16 v[106:109], v[160:163], v[194:197], v[106:109]
	v_mfma_f32_16x16x32_bf16 v[94:97], v[152:155], v[202:205], v[94:97]
	v_mfma_f32_16x16x32_bf16 v[90:93], v[160:163], v[202:205], v[90:93]
	v_mfma_f32_16x16x32_bf16 v[78:81], v[152:155], v[210:213], v[78:81]
	v_mfma_f32_16x16x32_bf16 v[74:77], v[160:163], v[210:213], v[74:77]
	v_mfma_f32_16x16x32_bf16 v[126:129], v[156:159], v[190:193], v[126:129]
	v_mfma_f32_16x16x32_bf16 v[122:125], v[164:167], v[190:193], v[122:125]
	v_mfma_f32_16x16x32_bf16 v[110:113], v[156:159], v[198:201], v[110:113]
	v_mfma_f32_16x16x32_bf16 v[106:109], v[164:167], v[198:201], v[106:109]
	v_mfma_f32_16x16x32_bf16 v[94:97], v[156:159], v[206:209], v[94:97]
	v_mfma_f32_16x16x32_bf16 v[90:93], v[164:167], v[206:209], v[90:93]
	v_mfma_f32_16x16x32_bf16 v[78:81], v[156:159], v[214:217], v[78:81]
	v_mfma_f32_16x16x32_bf16 v[74:77], v[164:167], v[214:217], v[74:77]
	v_mfma_f32_16x16x32_bf16 v[118:121], v[168:171], v[184:187], v[118:121]
	v_mfma_f32_16x16x32_bf16 v[114:117], v[176:179], v[184:187], v[114:117]
	v_mfma_f32_16x16x32_bf16 v[102:105], v[168:171], v[194:197], v[102:105]
	v_mfma_f32_16x16x32_bf16 v[98:101], v[176:179], v[194:197], v[98:101]
	v_mfma_f32_16x16x32_bf16 v[86:89], v[168:171], v[202:205], v[86:89]
	v_mfma_f32_16x16x32_bf16 v[82:85], v[176:179], v[202:205], v[82:85]
	v_mfma_f32_16x16x32_bf16 v[70:73], v[168:171], v[210:213], v[70:73]
	v_mfma_f32_16x16x32_bf16 v[66:69], v[176:179], v[210:213], v[66:69]
	v_mfma_f32_16x16x32_bf16 v[118:121], v[172:175], v[190:193], v[118:121]
	v_mfma_f32_16x16x32_bf16 v[114:117], v[180:183], v[190:193], v[114:117]
	v_mfma_f32_16x16x32_bf16 v[102:105], v[172:175], v[198:201], v[102:105]
	v_mfma_f32_16x16x32_bf16 v[98:101], v[180:183], v[198:201], v[98:101]
	v_mfma_f32_16x16x32_bf16 v[86:89], v[172:175], v[206:209], v[86:89]
	v_mfma_f32_16x16x32_bf16 v[82:85], v[180:183], v[206:209], v[82:85]
	v_mfma_f32_16x16x32_bf16 v[70:73], v[172:175], v[214:217], v[70:73]
	v_mfma_f32_16x16x32_bf16 v[66:69], v[180:183], v[214:217], v[66:69]
	s_setprio 0
	s_barrier
	s_add_i32 s50, s88, s36
	v_lshl_add_u64 v[218:219], s[24:25], 0, v[130:131]
	s_mov_b32 m0, s50
	ds_read_b128 v[184:187], v151 offset:16384
	ds_read_b128 v[190:193], v151 offset:17408
	ds_read_b128 v[194:197], v151 offset:18432
	ds_read_b128 v[198:201], v151 offset:19456
	ds_read_b128 v[202:205], v151 offset:20480
	ds_read_b128 v[206:209], v151 offset:21504
	ds_read_b128 v[210:213], v151 offset:22528
	ds_read_b128 v[214:217], v151 offset:23552
	global_load_lds_dwordx4 v[218:219], off
	s_add_i32 m0, s50, 0x2000
	s_add_u32 s50, s24, 0x40000
	v_lshl_add_u64 v[220:221], s[24:25], 0, v[132:133]
	s_addc_u32 s51, s25, 0
	s_add_i32 s52, s45, s36
	global_load_lds_dwordx4 v[220:221], off
	v_lshl_add_u64 v[222:223], s[50:51], 0, v[130:131]
	s_mov_b32 m0, s52
	v_lshl_add_u64 v[224:225], s[26:27], 0, v[136:137]
	global_load_lds_dwordx4 v[222:223], off
	v_lshl_add_u64 v[222:223], s[50:51], 0, v[132:133]
	s_add_i32 m0, s52, 0x2000
	s_nop 0
	global_load_lds_dwordx4 v[222:223], off
	v_lshl_add_u64 v[222:223], s[26:27], 0, v[134:135]
	s_mov_b32 m0, s37
	s_nop 0
	global_load_lds_dwordx4 v[222:223], off
	s_mov_b32 m0, s38
	s_nop 0
	global_load_lds_dwordx4 v[224:225], off
	s_waitcnt vmcnt(8)
	s_waitcnt lgkmcnt(0)
	s_barrier
	s_setprio 1
	s_waitcnt lgkmcnt(0)
	v_mfma_f32_16x16x32_bf16 v[62:65], v[152:155], v[184:187], v[62:65]
	v_mfma_f32_16x16x32_bf16 v[58:61], v[160:163], v[184:187], v[58:61]
	v_mfma_f32_16x16x32_bf16 v[46:49], v[152:155], v[194:197], v[46:49]
	v_mfma_f32_16x16x32_bf16 v[42:45], v[160:163], v[194:197], v[42:45]
	v_mfma_f32_16x16x32_bf16 v[30:33], v[152:155], v[202:205], v[30:33]
	v_mfma_f32_16x16x32_bf16 v[26:29], v[160:163], v[202:205], v[26:29]
	v_mfma_f32_16x16x32_bf16 v[14:17], v[152:155], v[210:213], v[14:17]
	v_mfma_f32_16x16x32_bf16 v[10:13], v[160:163], v[210:213], v[10:13]
	v_mfma_f32_16x16x32_bf16 v[62:65], v[156:159], v[190:193], v[62:65]
	v_mfma_f32_16x16x32_bf16 v[58:61], v[164:167], v[190:193], v[58:61]
	v_mfma_f32_16x16x32_bf16 v[46:49], v[156:159], v[198:201], v[46:49]
	v_mfma_f32_16x16x32_bf16 v[42:45], v[164:167], v[198:201], v[42:45]
	v_mfma_f32_16x16x32_bf16 v[30:33], v[156:159], v[206:209], v[30:33]
	v_mfma_f32_16x16x32_bf16 v[26:29], v[164:167], v[206:209], v[26:29]
	v_mfma_f32_16x16x32_bf16 v[14:17], v[156:159], v[214:217], v[14:17]
	v_mfma_f32_16x16x32_bf16 v[10:13], v[164:167], v[214:217], v[10:13]
	v_mfma_f32_16x16x32_bf16 v[54:57], v[168:171], v[184:187], v[54:57]
	v_mfma_f32_16x16x32_bf16 v[50:53], v[176:179], v[184:187], v[50:53]
	v_mfma_f32_16x16x32_bf16 v[38:41], v[168:171], v[194:197], v[38:41]
	v_mfma_f32_16x16x32_bf16 v[34:37], v[176:179], v[194:197], v[34:37]
	v_mfma_f32_16x16x32_bf16 v[22:25], v[168:171], v[202:205], v[22:25]
	v_mfma_f32_16x16x32_bf16 v[18:21], v[176:179], v[202:205], v[18:21]
	v_mfma_f32_16x16x32_bf16 v[6:9], v[168:171], v[210:213], v[6:9]
	v_mfma_f32_16x16x32_bf16 v[2:5], v[176:179], v[210:213], v[2:5]
	v_mfma_f32_16x16x32_bf16 v[54:57], v[172:175], v[190:193], v[54:57]
	v_mfma_f32_16x16x32_bf16 v[50:53], v[180:183], v[190:193], v[50:53]
	v_mfma_f32_16x16x32_bf16 v[38:41], v[172:175], v[198:201], v[38:41]
	v_mfma_f32_16x16x32_bf16 v[34:37], v[180:183], v[198:201], v[34:37]
	v_mfma_f32_16x16x32_bf16 v[22:25], v[172:175], v[206:209], v[22:25]
	v_mfma_f32_16x16x32_bf16 v[18:21], v[180:183], v[206:209], v[18:21]
	v_mfma_f32_16x16x32_bf16 v[6:9], v[172:175], v[214:217], v[6:9]
	v_mfma_f32_16x16x32_bf16 v[2:5], v[180:183], v[214:217], v[2:5]
	s_setprio 0
	s_barrier
	s_add_i32 s50, 0, 0x18000
	s_add_i32 s51, 0, 0x1c000
	v_add_u32_e32 v164, s50, v150
	v_add_u32_e32 v180, s51, v150
	ds_read_b128 v[152:155], v164
	ds_read_b128 v[156:159], v164 offset:1024
	ds_read_b128 v[160:163], v164 offset:2048
	ds_read_b128 v[164:167], v164 offset:3072
	ds_read_b128 v[168:171], v180
	ds_read_b128 v[172:175], v180 offset:1024
	ds_read_b128 v[176:179], v180 offset:2048
	ds_read_b128 v[180:183], v180 offset:3072
	s_add_u32 s26, s26, 0x40000
	s_addc_u32 s27, s27, 0
	s_mov_b32 m0, s39
	v_lshl_add_u64 v[226:227], s[26:27], 0, v[134:135]
	ds_read_b128 v[184:187], v151 offset:32768
	ds_read_b128 v[190:193], v151 offset:33792
	ds_read_b128 v[194:197], v151 offset:34816
	ds_read_b128 v[198:201], v151 offset:35840
	ds_read_b128 v[202:205], v151 offset:36864
	ds_read_b128 v[206:209], v151 offset:37888
	ds_read_b128 v[210:213], v151 offset:38912
	ds_read_b128 v[214:217], v151 offset:39936
	global_load_lds_dwordx4 v[226:227], off
	v_lshl_add_u64 v[226:227], s[26:27], 0, v[136:137]
	s_mov_b32 m0, s41
	s_nop 0
	global_load_lds_dwordx4 v[226:227], off
	s_waitcnt vmcnt(8)
	s_waitcnt lgkmcnt(0)
	s_barrier
	s_setprio 1
	s_waitcnt lgkmcnt(0)
	v_mfma_f32_16x16x32_bf16 v[126:129], v[152:155], v[184:187], v[126:129]
	v_mfma_f32_16x16x32_bf16 v[122:125], v[160:163], v[184:187], v[122:125]
	v_mfma_f32_16x16x32_bf16 v[110:113], v[152:155], v[194:197], v[110:113]
	v_mfma_f32_16x16x32_bf16 v[106:109], v[160:163], v[194:197], v[106:109]
	v_mfma_f32_16x16x32_bf16 v[94:97], v[152:155], v[202:205], v[94:97]
	v_mfma_f32_16x16x32_bf16 v[90:93], v[160:163], v[202:205], v[90:93]
	v_mfma_f32_16x16x32_bf16 v[78:81], v[152:155], v[210:213], v[78:81]
	v_mfma_f32_16x16x32_bf16 v[74:77], v[160:163], v[210:213], v[74:77]
	v_mfma_f32_16x16x32_bf16 v[126:129], v[156:159], v[190:193], v[126:129]
	v_mfma_f32_16x16x32_bf16 v[122:125], v[164:167], v[190:193], v[122:125]
	v_mfma_f32_16x16x32_bf16 v[110:113], v[156:159], v[198:201], v[110:113]
	v_mfma_f32_16x16x32_bf16 v[106:109], v[164:167], v[198:201], v[106:109]
	v_mfma_f32_16x16x32_bf16 v[94:97], v[156:159], v[206:209], v[94:97]
	v_mfma_f32_16x16x32_bf16 v[90:93], v[164:167], v[206:209], v[90:93]
	v_mfma_f32_16x16x32_bf16 v[78:81], v[156:159], v[214:217], v[78:81]
	v_mfma_f32_16x16x32_bf16 v[74:77], v[164:167], v[214:217], v[74:77]
	v_mfma_f32_16x16x32_bf16 v[118:121], v[168:171], v[184:187], v[118:121]
	v_mfma_f32_16x16x32_bf16 v[114:117], v[176:179], v[184:187], v[114:117]
	v_mfma_f32_16x16x32_bf16 v[102:105], v[168:171], v[194:197], v[102:105]
	v_mfma_f32_16x16x32_bf16 v[98:101], v[176:179], v[194:197], v[98:101]
	v_mfma_f32_16x16x32_bf16 v[86:89], v[168:171], v[202:205], v[86:89]
	v_mfma_f32_16x16x32_bf16 v[82:85], v[176:179], v[202:205], v[82:85]
	v_mfma_f32_16x16x32_bf16 v[70:73], v[168:171], v[210:213], v[70:73]
	v_mfma_f32_16x16x32_bf16 v[66:69], v[176:179], v[210:213], v[66:69]
	v_mfma_f32_16x16x32_bf16 v[118:121], v[172:175], v[190:193], v[118:121]
	v_mfma_f32_16x16x32_bf16 v[114:117], v[180:183], v[190:193], v[114:117]
	v_mfma_f32_16x16x32_bf16 v[102:105], v[172:175], v[198:201], v[102:105]
	v_mfma_f32_16x16x32_bf16 v[98:101], v[180:183], v[198:201], v[98:101]
	v_mfma_f32_16x16x32_bf16 v[86:89], v[172:175], v[206:209], v[86:89]
	v_mfma_f32_16x16x32_bf16 v[82:85], v[180:183], v[206:209], v[82:85]
	v_mfma_f32_16x16x32_bf16 v[70:73], v[172:175], v[214:217], v[70:73]
	v_mfma_f32_16x16x32_bf16 v[66:69], v[180:183], v[214:217], v[66:69]
	s_setprio 0
	s_barrier
	s_add_i32 s26, s50, s36
	v_lshl_add_u64 v[218:219], v[218:219], 0, s[10:11]
	s_mov_b32 m0, s26
	ds_read_b128 v[184:187], v151 offset:49152
	ds_read_b128 v[190:193], v151 offset:50176
	ds_read_b128 v[194:197], v151 offset:51200
	ds_read_b128 v[198:201], v151 offset:52224
	ds_read_b128 v[202:205], v151 offset:53248
	ds_read_b128 v[206:209], v151 offset:54272
	ds_read_b128 v[210:213], v151 offset:55296
	ds_read_b128 v[214:217], v151 offset:56320
	global_load_lds_dwordx4 v[218:219], off
	s_add_i32 m0, s26, 0x2000
	s_add_u32 s24, s24, 0x40080
	v_lshl_add_u64 v[218:219], v[220:221], 0, s[10:11]
	s_addc_u32 s25, s25, 0
	s_add_i32 s26, s51, s36
	global_load_lds_dwordx4 v[218:219], off
	v_lshl_add_u64 v[218:219], s[24:25], 0, v[130:131]
	s_mov_b32 m0, s26
	s_nop 0
	global_load_lds_dwordx4 v[218:219], off
	v_lshl_add_u64 v[218:219], s[24:25], 0, v[132:133]
	s_add_i32 m0, s26, 0x2000
	s_nop 0
	global_load_lds_dwordx4 v[218:219], off
	v_lshl_add_u64 v[218:219], v[222:223], 0, s[10:11]
	s_mov_b32 m0, s42
	s_nop 0
	global_load_lds_dwordx4 v[218:219], off
	v_lshl_add_u64 v[218:219], v[224:225], 0, s[10:11]
	s_mov_b32 m0, s43
	s_nop 0
	global_load_lds_dwordx4 v[218:219], off
	s_waitcnt vmcnt(8)
	s_waitcnt lgkmcnt(0)
	s_barrier
	s_setprio 1
	s_waitcnt lgkmcnt(0)
	v_mfma_f32_16x16x32_bf16 v[62:65], v[152:155], v[184:187], v[62:65]
	v_mfma_f32_16x16x32_bf16 v[58:61], v[160:163], v[184:187], v[58:61]
	v_mfma_f32_16x16x32_bf16 v[46:49], v[152:155], v[194:197], v[46:49]
	v_mfma_f32_16x16x32_bf16 v[42:45], v[160:163], v[194:197], v[42:45]
	v_mfma_f32_16x16x32_bf16 v[30:33], v[152:155], v[202:205], v[30:33]
	v_mfma_f32_16x16x32_bf16 v[26:29], v[160:163], v[202:205], v[26:29]
	v_mfma_f32_16x16x32_bf16 v[14:17], v[152:155], v[210:213], v[14:17]
	v_mfma_f32_16x16x32_bf16 v[10:13], v[160:163], v[210:213], v[10:13]
	v_mfma_f32_16x16x32_bf16 v[62:65], v[156:159], v[190:193], v[62:65]
	v_mfma_f32_16x16x32_bf16 v[58:61], v[164:167], v[190:193], v[58:61]
	v_mfma_f32_16x16x32_bf16 v[46:49], v[156:159], v[198:201], v[46:49]
	v_mfma_f32_16x16x32_bf16 v[42:45], v[164:167], v[198:201], v[42:45]
	v_mfma_f32_16x16x32_bf16 v[30:33], v[156:159], v[206:209], v[30:33]
	v_mfma_f32_16x16x32_bf16 v[26:29], v[164:167], v[206:209], v[26:29]
	v_mfma_f32_16x16x32_bf16 v[14:17], v[156:159], v[214:217], v[14:17]
	v_mfma_f32_16x16x32_bf16 v[10:13], v[164:167], v[214:217], v[10:13]
	v_mfma_f32_16x16x32_bf16 v[54:57], v[168:171], v[184:187], v[54:57]
	v_mfma_f32_16x16x32_bf16 v[50:53], v[176:179], v[184:187], v[50:53]
	v_mfma_f32_16x16x32_bf16 v[38:41], v[168:171], v[194:197], v[38:41]
	v_mfma_f32_16x16x32_bf16 v[34:37], v[176:179], v[194:197], v[34:37]
	v_mfma_f32_16x16x32_bf16 v[22:25], v[168:171], v[202:205], v[22:25]
	v_mfma_f32_16x16x32_bf16 v[18:21], v[176:179], v[202:205], v[18:21]
	v_mfma_f32_16x16x32_bf16 v[6:9], v[168:171], v[210:213], v[6:9]
	v_mfma_f32_16x16x32_bf16 v[2:5], v[176:179], v[210:213], v[2:5]
	v_mfma_f32_16x16x32_bf16 v[54:57], v[172:175], v[190:193], v[54:57]
	v_mfma_f32_16x16x32_bf16 v[50:53], v[180:183], v[190:193], v[50:53]
	v_mfma_f32_16x16x32_bf16 v[38:41], v[172:175], v[198:201], v[38:41]
	v_mfma_f32_16x16x32_bf16 v[34:37], v[180:183], v[198:201], v[34:37]
	v_mfma_f32_16x16x32_bf16 v[22:25], v[172:175], v[206:209], v[22:25]
	v_mfma_f32_16x16x32_bf16 v[18:21], v[180:183], v[206:209], v[18:21]
	v_mfma_f32_16x16x32_bf16 v[6:9], v[172:175], v[214:217], v[6:9]
	v_mfma_f32_16x16x32_bf16 v[2:5], v[180:183], v[214:217], v[2:5]
	s_setprio 0
	s_barrier
	s_add_i32 s49, s49, 2
	s_add_u32 s22, s22, 0x100
	s_addc_u32 s23, s23, 0
	s_cmp_gt_u32 s49, 13
	s_cbranch_scc0 .LBB0_946
	s_add_u32 s22, s13, 0xffffff00
	s_addc_u32 s23, s48, -1
	s_andn2_b64 vcc, exec, s[4:5]
	s_cbranch_vccnz .LBB0_937
	v_mov_b32_e32 v2, 0
	s_mov_b32 s18, s46
	s_mov_b32 s6, s12
	s_mov_b64 s[8:9], s[20:21]
	s_mov_b32 s44, s47
	v_mov_b32_e32 v3, v2
	v_mov_b32_e32 v4, v2
	v_mov_b32_e32 v5, v2
	v_mov_b32_e32 v6, v2
	v_mov_b32_e32 v7, v2
	v_mov_b32_e32 v8, v2
	v_mov_b32_e32 v9, v2
	v_mov_b32_e32 v18, v2
	v_mov_b32_e32 v19, v2
	v_mov_b32_e32 v20, v2
	v_mov_b32_e32 v21, v2
	v_mov_b32_e32 v22, v2
	v_mov_b32_e32 v23, v2
	v_mov_b32_e32 v24, v2
	v_mov_b32_e32 v25, v2
	v_mov_b32_e32 v34, v2
	v_mov_b32_e32 v35, v2
	v_mov_b32_e32 v36, v2
	v_mov_b32_e32 v37, v2
	v_mov_b32_e32 v38, v2
	v_mov_b32_e32 v39, v2
	v_mov_b32_e32 v40, v2
	v_mov_b32_e32 v41, v2
	v_mov_b32_e32 v50, v2
	v_mov_b32_e32 v51, v2
	v_mov_b32_e32 v52, v2
	v_mov_b32_e32 v53, v2
	v_mov_b32_e32 v54, v2
	v_mov_b32_e32 v55, v2
	v_mov_b32_e32 v56, v2
	v_mov_b32_e32 v57, v2
	v_mov_b32_e32 v10, v2
	v_mov_b32_e32 v11, v2
	v_mov_b32_e32 v12, v2
	v_mov_b32_e32 v13, v2
	v_mov_b32_e32 v14, v2
	v_mov_b32_e32 v15, v2
	v_mov_b32_e32 v16, v2
	v_mov_b32_e32 v17, v2
	v_mov_b32_e32 v26, v2
	v_mov_b32_e32 v27, v2
	v_mov_b32_e32 v28, v2
	v_mov_b32_e32 v29, v2
	v_mov_b32_e32 v30, v2
	v_mov_b32_e32 v31, v2
	v_mov_b32_e32 v32, v2
	v_mov_b32_e32 v33, v2
	v_mov_b32_e32 v42, v2
	v_mov_b32_e32 v43, v2
	v_mov_b32_e32 v44, v2
	v_mov_b32_e32 v45, v2
	v_mov_b32_e32 v46, v2
	v_mov_b32_e32 v47, v2
	v_mov_b32_e32 v48, v2
	v_mov_b32_e32 v49, v2
	v_mov_b32_e32 v58, v2
	v_mov_b32_e32 v59, v2
	v_mov_b32_e32 v60, v2
	v_mov_b32_e32 v61, v2
	v_mov_b32_e32 v62, v2
	v_mov_b32_e32 v63, v2
	v_mov_b32_e32 v64, v2
	v_mov_b32_e32 v65, v2
	v_mov_b32_e32 v66, v2
	v_mov_b32_e32 v67, v2
	v_mov_b32_e32 v68, v2
	v_mov_b32_e32 v69, v2
	v_mov_b32_e32 v70, v2
	v_mov_b32_e32 v71, v2
	v_mov_b32_e32 v72, v2
	v_mov_b32_e32 v73, v2
	v_mov_b32_e32 v82, v2
	v_mov_b32_e32 v83, v2
	v_mov_b32_e32 v84, v2
	v_mov_b32_e32 v85, v2
	v_mov_b32_e32 v86, v2
	v_mov_b32_e32 v87, v2
	v_mov_b32_e32 v88, v2
	v_mov_b32_e32 v89, v2
	v_mov_b32_e32 v98, v2
	v_mov_b32_e32 v99, v2
	v_mov_b32_e32 v100, v2
	v_mov_b32_e32 v101, v2
	v_mov_b32_e32 v102, v2
	v_mov_b32_e32 v103, v2
	v_mov_b32_e32 v104, v2
	v_mov_b32_e32 v105, v2
	v_mov_b32_e32 v114, v2
	v_mov_b32_e32 v115, v2
	v_mov_b32_e32 v116, v2
	v_mov_b32_e32 v117, v2
	v_mov_b32_e32 v118, v2
	v_mov_b32_e32 v119, v2
	v_mov_b32_e32 v120, v2
	v_mov_b32_e32 v121, v2
	v_mov_b32_e32 v74, v2
	v_mov_b32_e32 v75, v2
	v_mov_b32_e32 v76, v2
	v_mov_b32_e32 v77, v2
	v_mov_b32_e32 v78, v2
	v_mov_b32_e32 v79, v2
	v_mov_b32_e32 v80, v2
	v_mov_b32_e32 v81, v2
	v_mov_b32_e32 v90, v2
	v_mov_b32_e32 v91, v2
	v_mov_b32_e32 v92, v2
	v_mov_b32_e32 v93, v2
	v_mov_b32_e32 v94, v2
	v_mov_b32_e32 v95, v2
	v_mov_b32_e32 v96, v2
	v_mov_b32_e32 v97, v2
	v_mov_b32_e32 v106, v2
	v_mov_b32_e32 v107, v2
	v_mov_b32_e32 v108, v2
	v_mov_b32_e32 v109, v2
	v_mov_b32_e32 v110, v2
	v_mov_b32_e32 v111, v2
	v_mov_b32_e32 v112, v2
	v_mov_b32_e32 v113, v2
	v_mov_b32_e32 v122, v2
	v_mov_b32_e32 v123, v2
	v_mov_b32_e32 v124, v2
	v_mov_b32_e32 v125, v2
	v_mov_b32_e32 v126, v2
	v_mov_b32_e32 v127, v2
	v_mov_b32_e32 v128, v2
	v_mov_b32_e32 v129, v2
	s_andn2_b64 vcc, exec, s[0:1]
	s_cbranch_vccnz .LBB0_938
